# final RMSNorm loop rewritten (batched loads), ssm_xend and GLU weight loads batched, permlane32 swap instead of bpermute in forgetting attention
# speedup vs baseline: 1.0453x; 1.0060x over previous
; DI int get_tid() { int t = __builtin_amdgcn_workitem_id_x(); asm volatile("" : "+v"(t)); return t; }
; DI float shx(float v, int lane, int mask) { return __int_as_float(__builtin_amdgcn_ds_bpermute((lane ^ mask) << 2, __float_as_int(v))); }
; DI float wave_sum(float v) {
;   const int lane = get_tid() & 63;
; #pragma unroll
;   for (int o = 32; o >= 1; o >>= 1) v += shx(v, lane, o);
;   return v;
; }
; template <int WHICH>
; DI void norm_item(const CP& p, int l, int item) {
;     ...
;   for (int it = 0; it < 4; ++it) {
;     const int t = item * 32 + w * 4 + it;
;     const int b = t / S_;
;     fl4 xv[4];
;     float ssq = 0.f;
; #pragma unroll
;     for (int q = 0; q < 4; ++q) {
;       xv[q] = *(const fl4*)(xs + (size_t)t * 1024 + q * 256 + lane * 4);
;       ssq += xv[q].x * xv[q].x + xv[q].y * xv[q].y + xv[q].z * xv[q].z + xv[q].w * xv[q].w;
;     }
;     ssq = wave_sum(ssq);
;     const float rstd = __builtin_amdgcn_rsqf(ssq * (1.f / 1024.f) + 1e-6f);
;     if (WHICH == 3) {
; #pragma unroll
;       for (int q = 0; q < 4; ++q) {
;         fl4 g = *(const fl4*)(gain + q * 256 + lane * 4);
;         fl4 o;
;         o.x = xv[q].x * rstd * g.x; o.y = xv[q].y * rstd * g.y; o.z = xv[q].z * rstd * g.z; o.w = xv[q].w * rstd * g.w;
;         *(fl4*)(p.out + (size_t)t * 1024 + q * 256 + lane * 4) = o;
;       }
.LBB0_203:
	s_nop 0
	v_mov_b32_e32 v0, v202
	s_load_dwordx2 s[8:9], s[0:1], 0xd0
	v_lshlrev_b32_e32 v126, 2, v0
	s_waitcnt lgkmcnt(0)
	v_ashrrev_i32_e32 v1, 4, v0
	v_and_b32_e32 v1, -4, v1
	v_add_u32_e32 v20, s10, v1
	v_lshlrev_b32_e32 v0, 4, v0
	v_and_b32_e32 v32, 0x3f0, v0
	v_ashrrev_i32_e32 v21, 31, v20
	v_lshl_add_u64 v[18:19], s[8:9], 0, v[32:33]
	v_lshlrev_b64 v[24:25], 12, v[20:21]
	v_lshl_add_u64 v[0:1], v[18:19], 0, v[24:25]
	v_lshl_add_u64 v[16:17], s[6:7], 0, v[32:33]
	v_lshl_add_u64 v[8:9], v[16:17], 0, v[24:25]
	v_lshl_add_u64 v[2:3], v[0:1], 0, s[60:61]
	v_lshl_add_u64 v[10:11], v[8:9], 0, s[60:61]
	v_lshl_add_u64 v[4:5], v[2:3], 0, s[60:61]
	v_lshl_add_u64 v[12:13], v[10:11], 0, s[60:61]
	v_lshl_add_u64 v[6:7], v[4:5], 0, s[60:61]
	v_lshl_add_u64 v[14:15], v[12:13], 0, s[60:61]
	global_load_dwordx4 v[34:37], v[0:1], off
	global_load_dwordx4 v[38:41], v[0:1], off offset:1024
	global_load_dwordx4 v[42:45], v[0:1], off offset:2048
	global_load_dwordx4 v[46:49], v[0:1], off offset:3072
	global_load_dwordx4 v[50:53], v[2:3], off
	global_load_dwordx4 v[54:57], v[2:3], off offset:1024
	global_load_dwordx4 v[58:61], v[2:3], off offset:2048
	global_load_dwordx4 v[62:65], v[2:3], off offset:3072
	global_load_dwordx4 v[66:69], v[4:5], off
	global_load_dwordx4 v[70:73], v[4:5], off offset:1024
	global_load_dwordx4 v[74:77], v[4:5], off offset:2048
	global_load_dwordx4 v[78:81], v[4:5], off offset:3072
	global_load_dwordx4 v[82:85], v[6:7], off
	global_load_dwordx4 v[86:89], v[6:7], off offset:1024
	global_load_dwordx4 v[90:93], v[6:7], off offset:2048
	global_load_dwordx4 v[94:97], v[6:7], off offset:3072
	global_load_dwordx4 v[98:101], v32, s[4:5]
	global_load_dwordx4 v[102:105], v32, s[4:5] offset:1024
	global_load_dwordx4 v[106:109], v32, s[4:5] offset:2048
	global_load_dwordx4 v[110:113], v32, s[4:5] offset:3072
	s_add_i32 s11, s11, s34
	s_add_i32 s10, s10, s91
	s_waitcnt vmcnt(16)
	v_mul_f32_e32 v114, v35, v35
	v_fmac_f32_e32 v114, v34, v34
	v_fmac_f32_e32 v114, v36, v36
	v_fmac_f32_e32 v114, v37, v37
	v_fmac_f32_e32 v114, v39, v39
	v_fmac_f32_e32 v114, v38, v38
	v_fmac_f32_e32 v114, v40, v40
	v_fmac_f32_e32 v114, v41, v41
	v_fmac_f32_e32 v114, v43, v43
	v_fmac_f32_e32 v114, v42, v42
	v_fmac_f32_e32 v114, v44, v44
	v_fmac_f32_e32 v114, v45, v45
	v_fmac_f32_e32 v114, v47, v47
	v_fmac_f32_e32 v114, v46, v46
	v_fmac_f32_e32 v114, v48, v48
	v_fmac_f32_e32 v114, v49, v49
	s_waitcnt vmcnt(12)
	v_mul_f32_e32 v116, v51, v51
	v_fmac_f32_e32 v116, v50, v50
	v_fmac_f32_e32 v116, v52, v52
	v_fmac_f32_e32 v116, v53, v53
	v_fmac_f32_e32 v116, v55, v55
	v_fmac_f32_e32 v116, v54, v54
	v_fmac_f32_e32 v116, v56, v56
	v_fmac_f32_e32 v116, v57, v57
	v_fmac_f32_e32 v116, v59, v59
	v_fmac_f32_e32 v116, v58, v58
	v_fmac_f32_e32 v116, v60, v60
	v_fmac_f32_e32 v116, v61, v61
	v_fmac_f32_e32 v116, v63, v63
	v_fmac_f32_e32 v116, v62, v62
	v_fmac_f32_e32 v116, v64, v64
	v_fmac_f32_e32 v116, v65, v65
	s_waitcnt vmcnt(8)
	v_mul_f32_e32 v118, v67, v67
	v_fmac_f32_e32 v118, v66, v66
	v_fmac_f32_e32 v118, v68, v68
	v_fmac_f32_e32 v118, v69, v69
	v_fmac_f32_e32 v118, v71, v71
	v_fmac_f32_e32 v118, v70, v70
	v_fmac_f32_e32 v118, v72, v72
	v_fmac_f32_e32 v118, v73, v73
	v_fmac_f32_e32 v118, v75, v75
	v_fmac_f32_e32 v118, v74, v74
	v_fmac_f32_e32 v118, v76, v76
	v_fmac_f32_e32 v118, v77, v77
	v_fmac_f32_e32 v118, v79, v79
	v_fmac_f32_e32 v118, v78, v78
	v_fmac_f32_e32 v118, v80, v80
	v_fmac_f32_e32 v118, v81, v81
	s_waitcnt vmcnt(4)
	v_mul_f32_e32 v120, v83, v83
	v_fmac_f32_e32 v120, v82, v82
	v_fmac_f32_e32 v120, v84, v84
	v_fmac_f32_e32 v120, v85, v85
	v_fmac_f32_e32 v120, v87, v87
	v_fmac_f32_e32 v120, v86, v86
	v_fmac_f32_e32 v120, v88, v88
	v_fmac_f32_e32 v120, v89, v89
	v_fmac_f32_e32 v120, v91, v91
	v_fmac_f32_e32 v120, v90, v90
	v_fmac_f32_e32 v120, v92, v92
	v_fmac_f32_e32 v120, v93, v93
	v_fmac_f32_e32 v120, v95, v95
	v_fmac_f32_e32 v120, v94, v94
	v_fmac_f32_e32 v120, v96, v96
	v_fmac_f32_e32 v120, v97, v97
	v_bitop3_b32 v127, v126, s84, v211 bitop3:0x6c
	ds_bpermute_b32 v122, v127, v114
	ds_bpermute_b32 v123, v127, v116
	ds_bpermute_b32 v124, v127, v118
	ds_bpermute_b32 v125, v127, v120
	s_waitcnt lgkmcnt(0)
	v_add_f32_e32 v114, v114, v122
	v_add_f32_e32 v116, v116, v123
	v_add_f32_e32 v118, v118, v124
	v_add_f32_e32 v120, v120, v125
	v_bitop3_b32 v127, v126, 64, v211 bitop3:0x6c
	ds_bpermute_b32 v122, v127, v114
	ds_bpermute_b32 v123, v127, v116
	ds_bpermute_b32 v124, v127, v118
	ds_bpermute_b32 v125, v127, v120
	s_waitcnt lgkmcnt(0)
	v_add_f32_e32 v114, v114, v122
	v_add_f32_e32 v116, v116, v123
	v_add_f32_e32 v118, v118, v124
	v_add_f32_e32 v120, v120, v125
	v_bitop3_b32 v127, v126, 32, v211 bitop3:0x6c
	ds_bpermute_b32 v122, v127, v114
	ds_bpermute_b32 v123, v127, v116
	ds_bpermute_b32 v124, v127, v118
	ds_bpermute_b32 v125, v127, v120
	s_waitcnt lgkmcnt(0)
	v_add_f32_e32 v114, v114, v122
	v_add_f32_e32 v116, v116, v123
	v_add_f32_e32 v118, v118, v124
	v_add_f32_e32 v120, v120, v125
	v_bitop3_b32 v127, v126, 16, v211 bitop3:0x6c
	ds_bpermute_b32 v122, v127, v114
	ds_bpermute_b32 v123, v127, v116
	ds_bpermute_b32 v124, v127, v118
	ds_bpermute_b32 v125, v127, v120
	s_waitcnt lgkmcnt(0)
; template <int WHICH>
; DI void norm_item(const CP& p, int l, int item) {
;     ...
;     const float rstd = __builtin_amdgcn_rsqf(ssq * (1.f / 1024.f) + 1e-6f);
;     if (WHICH == 3) {
; #pragma unroll
;       for (int q = 0; q < 4; ++q) {
;         fl4 g = *(const fl4*)(gain + q * 256 + lane * 4);
;         fl4 o;
;         o.x = xv[q].x * rstd * g.x; o.y = xv[q].y * rstd * g.y; o.z = xv[q].z * rstd * g.z; o.w = xv[q].w * rstd * g.w;
;         *(fl4*)(p.out + (size_t)t * 1024 + q * 256 + lane * 4) = o;
;       }
; template <bool DRY>
; DI void run_phase(const CP& p, int ph, int l, char* smem) {
;     ...
;       for (int it = b0; it < T_ / 32; it += nb) norm_item<3>(p, 0, it);
	v_add_f32_e32 v114, v114, v122
	v_add_f32_e32 v116, v116, v123
	v_add_f32_e32 v118, v118, v124
	v_add_f32_e32 v120, v120, v125
	v_bitop3_b32 v127, v126, 8, v211 bitop3:0x6c
	ds_bpermute_b32 v122, v127, v114
	ds_bpermute_b32 v123, v127, v116
	ds_bpermute_b32 v124, v127, v118
	ds_bpermute_b32 v125, v127, v120
	s_waitcnt lgkmcnt(0)
	v_add_f32_e32 v114, v114, v122
	v_add_f32_e32 v116, v116, v123
	v_add_f32_e32 v118, v118, v124
	v_add_f32_e32 v120, v120, v125
	v_bitop3_b32 v127, v126, 4, v211 bitop3:0x6c
	ds_bpermute_b32 v122, v127, v114
	ds_bpermute_b32 v123, v127, v116
	ds_bpermute_b32 v124, v127, v118
	ds_bpermute_b32 v125, v127, v120
	s_waitcnt lgkmcnt(0)
	v_add_f32_e32 v114, v114, v122
	v_add_f32_e32 v116, v116, v123
	v_add_f32_e32 v118, v118, v124
	v_add_f32_e32 v120, v120, v125
	v_fmamk_f32 v114, v114, 0x3a800000, v203
	v_fmamk_f32 v116, v116, 0x3a800000, v203
	v_fmamk_f32 v118, v118, 0x3a800000, v203
	v_fmamk_f32 v120, v120, 0x3a800000, v203
	v_rsq_f32_e32 v114, v114
	v_rsq_f32_e32 v116, v116
	v_rsq_f32_e32 v118, v118
	v_rsq_f32_e32 v120, v120
	s_waitcnt vmcnt(0)
	v_pk_mul_f32 v[34:35], v[34:35], v[114:115] op_sel_hi:[1,0]
	v_pk_mul_f32 v[36:37], v[36:37], v[114:115] op_sel_hi:[1,0]
	v_pk_mul_f32 v[34:35], v[98:99], v[34:35]
	v_pk_mul_f32 v[36:37], v[100:101], v[36:37]
	global_store_dwordx4 v[8:9], v[34:37], off
	v_pk_mul_f32 v[38:39], v[38:39], v[114:115] op_sel_hi:[1,0]
	v_pk_mul_f32 v[40:41], v[40:41], v[114:115] op_sel_hi:[1,0]
	v_pk_mul_f32 v[38:39], v[102:103], v[38:39]
	v_pk_mul_f32 v[40:41], v[104:105], v[40:41]
	global_store_dwordx4 v[8:9], v[38:41], off offset:1024
	v_pk_mul_f32 v[42:43], v[42:43], v[114:115] op_sel_hi:[1,0]
	v_pk_mul_f32 v[44:45], v[44:45], v[114:115] op_sel_hi:[1,0]
	v_pk_mul_f32 v[42:43], v[106:107], v[42:43]
	v_pk_mul_f32 v[44:45], v[108:109], v[44:45]
	global_store_dwordx4 v[8:9], v[42:45], off offset:2048
	v_pk_mul_f32 v[46:47], v[46:47], v[114:115] op_sel_hi:[1,0]
	v_pk_mul_f32 v[48:49], v[48:49], v[114:115] op_sel_hi:[1,0]
	v_pk_mul_f32 v[46:47], v[110:111], v[46:47]
	v_pk_mul_f32 v[48:49], v[112:113], v[48:49]
	global_store_dwordx4 v[8:9], v[46:49], off offset:3072
	v_pk_mul_f32 v[50:51], v[50:51], v[116:117] op_sel_hi:[1,0]
	v_pk_mul_f32 v[52:53], v[52:53], v[116:117] op_sel_hi:[1,0]
	v_pk_mul_f32 v[50:51], v[98:99], v[50:51]
	v_pk_mul_f32 v[52:53], v[100:101], v[52:53]
	global_store_dwordx4 v[10:11], v[50:53], off
	v_pk_mul_f32 v[54:55], v[54:55], v[116:117] op_sel_hi:[1,0]
	v_pk_mul_f32 v[56:57], v[56:57], v[116:117] op_sel_hi:[1,0]
	v_pk_mul_f32 v[54:55], v[102:103], v[54:55]
	v_pk_mul_f32 v[56:57], v[104:105], v[56:57]
	global_store_dwordx4 v[10:11], v[54:57], off offset:1024
	v_pk_mul_f32 v[58:59], v[58:59], v[116:117] op_sel_hi:[1,0]
	v_pk_mul_f32 v[60:61], v[60:61], v[116:117] op_sel_hi:[1,0]
	v_pk_mul_f32 v[58:59], v[106:107], v[58:59]
	v_pk_mul_f32 v[60:61], v[108:109], v[60:61]
	global_store_dwordx4 v[10:11], v[58:61], off offset:2048
	v_pk_mul_f32 v[62:63], v[62:63], v[116:117] op_sel_hi:[1,0]
	v_pk_mul_f32 v[64:65], v[64:65], v[116:117] op_sel_hi:[1,0]
	v_pk_mul_f32 v[62:63], v[110:111], v[62:63]
	v_pk_mul_f32 v[64:65], v[112:113], v[64:65]
	global_store_dwordx4 v[10:11], v[62:65], off offset:3072
	v_pk_mul_f32 v[66:67], v[66:67], v[118:119] op_sel_hi:[1,0]
	v_pk_mul_f32 v[68:69], v[68:69], v[118:119] op_sel_hi:[1,0]
	v_pk_mul_f32 v[66:67], v[98:99], v[66:67]
	v_pk_mul_f32 v[68:69], v[100:101], v[68:69]
	global_store_dwordx4 v[12:13], v[66:69], off
	v_pk_mul_f32 v[70:71], v[70:71], v[118:119] op_sel_hi:[1,0]
	v_pk_mul_f32 v[72:73], v[72:73], v[118:119] op_sel_hi:[1,0]
	v_pk_mul_f32 v[70:71], v[102:103], v[70:71]
	v_pk_mul_f32 v[72:73], v[104:105], v[72:73]
	global_store_dwordx4 v[12:13], v[70:73], off offset:1024
	v_pk_mul_f32 v[74:75], v[74:75], v[118:119] op_sel_hi:[1,0]
	v_pk_mul_f32 v[76:77], v[76:77], v[118:119] op_sel_hi:[1,0]
	v_pk_mul_f32 v[74:75], v[106:107], v[74:75]
	v_pk_mul_f32 v[76:77], v[108:109], v[76:77]
	global_store_dwordx4 v[12:13], v[74:77], off offset:2048
	v_pk_mul_f32 v[78:79], v[78:79], v[118:119] op_sel_hi:[1,0]
	v_pk_mul_f32 v[80:81], v[80:81], v[118:119] op_sel_hi:[1,0]
	v_pk_mul_f32 v[78:79], v[110:111], v[78:79]
	v_pk_mul_f32 v[80:81], v[112:113], v[80:81]
	global_store_dwordx4 v[12:13], v[78:81], off offset:3072
	v_pk_mul_f32 v[82:83], v[82:83], v[120:121] op_sel_hi:[1,0]
	v_pk_mul_f32 v[84:85], v[84:85], v[120:121] op_sel_hi:[1,0]
	v_pk_mul_f32 v[82:83], v[98:99], v[82:83]
	v_pk_mul_f32 v[84:85], v[100:101], v[84:85]
	global_store_dwordx4 v[14:15], v[82:85], off
	v_pk_mul_f32 v[86:87], v[86:87], v[120:121] op_sel_hi:[1,0]
	v_pk_mul_f32 v[88:89], v[88:89], v[120:121] op_sel_hi:[1,0]
	v_pk_mul_f32 v[86:87], v[102:103], v[86:87]
	v_pk_mul_f32 v[88:89], v[104:105], v[88:89]
	global_store_dwordx4 v[14:15], v[86:89], off offset:1024
	v_pk_mul_f32 v[90:91], v[90:91], v[120:121] op_sel_hi:[1,0]
	v_pk_mul_f32 v[92:93], v[92:93], v[120:121] op_sel_hi:[1,0]
	v_pk_mul_f32 v[90:91], v[106:107], v[90:91]
	v_pk_mul_f32 v[92:93], v[108:109], v[92:93]
	global_store_dwordx4 v[14:15], v[90:93], off offset:2048
	v_pk_mul_f32 v[94:95], v[94:95], v[120:121] op_sel_hi:[1,0]
	v_pk_mul_f32 v[96:97], v[96:97], v[120:121] op_sel_hi:[1,0]
	v_pk_mul_f32 v[94:95], v[110:111], v[94:95]
	v_pk_mul_f32 v[96:97], v[112:113], v[96:97]
	global_store_dwordx4 v[14:15], v[94:97], off offset:3072
	s_cmpk_lt_i32 s11, 0x400
	s_cbranch_scc1 .LBB0_203

; #define MFMA16(a, b, c) __builtin_amdgcn_mfma_f32_16x16x32_bf16((a), (b), (c), 0, 0, 0)
; DI unsigned pk2(float a, float b) { f2_t v = {a, b}; bf2_t r = __builtin_convertvector(v, bf2_t); return __builtin_bit_cast(unsigned, r); }
; DI void ssm_out_item(const CP& p, int l, int item, char* smem) {
;     ...
; #pragma unroll 8
;       for (int s2 = 0; s2 < 32; ++s2) {
;         const fl2 bu = {__uint_as_float((unsigned)sX[s2 * 136 + lane] << 16), __uint_as_float((unsigned)sX[s2 * 136 + 64 + lane] << 16)};
;         const fl2 xs = {-x.y, x.x};
;         x = x * a_r + xs * a_i + bu;
;         const unsigned pkx = pk2(x.x, x.y);
;         sX[s2 * 136 + lane] = (u16)(pkx & 0xffffu);
;         sX[s2 * 136 + 64 + lane] = (u16)(pkx >> 16);
;       }
;       __syncthreads();
;       f32x4v ya[2];
; #pragma unroll
;       for (int nb = 0; nb < 2; ++nb) {
;         ya[nb] = (f32x4v){0.f, 0.f, 0.f, 0.f};
; #pragma unroll
;         for (int ks = 0; ks < 4; ++ks) {
;           bf16x8 xb = *(const bf16x8*)(sX + (nb * 16 + l16) * 136 + ks * 32 + q4 * 8);
;           ya[nb] = MFMA16(cf[ks], xb, ya[nb]);
;         }
;       }
; #pragma unroll
;       for (int nb = 0; nb < 2; ++nb) {
;         const int s = sub * 32 + nb * 16 + l16;
;         const u32x2 uu = *(const u32x2*)(p.R + (tok0 + s) * TMW + 1408 + g * 16 + q4 * 4);
.LBB0_334:
	v_add_u32_e32 v6, s39, v32
	ds_read_u16 v100, v6
	ds_read_u16 v101, v6 offset:128
	ds_read_u16 v102, v6 offset:272
	ds_read_u16 v103, v6 offset:400
	ds_read_u16 v104, v6 offset:544
	ds_read_u16 v105, v6 offset:672
	ds_read_u16 v106, v6 offset:816
	ds_read_u16 v107, v6 offset:944
	s_addk_i32 s39, 0x880
	v_xor_b32_e32 v2, 0x80000000, v83
	v_mov_b32_e32 v3, v82
	v_pk_mul_f32 v[2:3], v[74:75], v[2:3]
	s_waitcnt lgkmcnt(6)
	v_lshlrev_b32_e32 v100, 16, v100
	v_lshlrev_b32_e32 v101, 16, v101
	v_pk_fma_f32 v[2:3], v[80:81], v[82:83], v[2:3]
	s_nop 0
	v_pk_add_f32 v[0:1], v[2:3], v[100:101]
	s_nop 0
	v_cvt_pk_bf16_f32 v2, v0, v1
	ds_write_b16 v6, v2
	ds_write_b16_d16_hi v6, v2 offset:128
	v_xor_b32_e32 v4, 0x80000000, v1
	v_mov_b32_e32 v5, v0
	v_pk_mul_f32 v[4:5], v[74:75], v[4:5]
	s_waitcnt lgkmcnt(6)
	v_lshlrev_b32_e32 v102, 16, v102
	v_lshlrev_b32_e32 v103, 16, v103
	v_pk_fma_f32 v[0:1], v[80:81], v[0:1], v[4:5]
	s_nop 0
	v_pk_add_f32 v[0:1], v[0:1], v[102:103]
	s_nop 0
	v_cvt_pk_bf16_f32 v2, v0, v1
	ds_write_b16 v6, v2 offset:272
	ds_write_b16_d16_hi v6, v2 offset:400
	v_xor_b32_e32 v4, 0x80000000, v1
	v_mov_b32_e32 v5, v0
	v_pk_mul_f32 v[4:5], v[74:75], v[4:5]
	s_waitcnt lgkmcnt(6)
	v_lshlrev_b32_e32 v104, 16, v104
	v_lshlrev_b32_e32 v105, 16, v105
	v_pk_fma_f32 v[0:1], v[80:81], v[0:1], v[4:5]
	s_nop 0
	v_pk_add_f32 v[0:1], v[0:1], v[104:105]
	s_nop 0
	v_cvt_pk_bf16_f32 v2, v0, v1
	ds_write_b16 v6, v2 offset:544
	ds_write_b16_d16_hi v6, v2 offset:672
	v_xor_b32_e32 v4, 0x80000000, v1
	v_mov_b32_e32 v5, v0
	v_pk_mul_f32 v[4:5], v[74:75], v[4:5]
	s_waitcnt lgkmcnt(6)
	v_lshlrev_b32_e32 v106, 16, v106
	v_lshlrev_b32_e32 v107, 16, v107
	v_pk_fma_f32 v[0:1], v[80:81], v[0:1], v[4:5]
	s_nop 0
	v_pk_add_f32 v[0:1], v[0:1], v[106:107]
	s_nop 0
	v_cvt_pk_bf16_f32 v2, v0, v1
	ds_write_b16 v6, v2 offset:816
	ds_write_b16_d16_hi v6, v2 offset:944
	ds_read_u16 v108, v6 offset:1088
	ds_read_u16 v109, v6 offset:1216
	ds_read_u16 v110, v6 offset:1360
	ds_read_u16 v111, v6 offset:1488
	ds_read_u16 v112, v6 offset:1632
	ds_read_u16 v113, v6 offset:1760
	ds_read_u16 v114, v6 offset:1904
	ds_read_u16 v115, v6 offset:2032
	v_xor_b32_e32 v4, 0x80000000, v1
	v_mov_b32_e32 v5, v0
	v_pk_mul_f32 v[4:5], v[74:75], v[4:5]
	s_waitcnt lgkmcnt(6)
	v_lshlrev_b32_e32 v108, 16, v108
	v_lshlrev_b32_e32 v109, 16, v109
	v_pk_fma_f32 v[0:1], v[80:81], v[0:1], v[4:5]
	s_nop 0
	v_pk_add_f32 v[0:1], v[0:1], v[108:109]
	s_nop 0
	v_cvt_pk_bf16_f32 v2, v0, v1
	ds_write_b16 v6, v2 offset:1088
	ds_write_b16_d16_hi v6, v2 offset:1216
	v_xor_b32_e32 v4, 0x80000000, v1
	v_mov_b32_e32 v5, v0
	v_pk_mul_f32 v[4:5], v[74:75], v[4:5]
	s_waitcnt lgkmcnt(6)
	v_lshlrev_b32_e32 v110, 16, v110
	v_lshlrev_b32_e32 v111, 16, v111
	v_pk_fma_f32 v[0:1], v[80:81], v[0:1], v[4:5]
	s_nop 0
	v_pk_add_f32 v[0:1], v[0:1], v[110:111]
	s_nop 0
	v_cvt_pk_bf16_f32 v2, v0, v1
	ds_write_b16 v6, v2 offset:1360
	ds_write_b16_d16_hi v6, v2 offset:1488
	v_xor_b32_e32 v4, 0x80000000, v1
	v_mov_b32_e32 v5, v0
	v_pk_mul_f32 v[4:5], v[74:75], v[4:5]
	s_waitcnt lgkmcnt(6)
	v_lshlrev_b32_e32 v112, 16, v112
	v_lshlrev_b32_e32 v113, 16, v113
	v_pk_fma_f32 v[0:1], v[80:81], v[0:1], v[4:5]
	s_nop 0
	v_pk_add_f32 v[0:1], v[0:1], v[112:113]
	s_nop 0
	v_cvt_pk_bf16_f32 v2, v0, v1
	ds_write_b16 v6, v2 offset:1632
	ds_write_b16_d16_hi v6, v2 offset:1760
	v_xor_b32_e32 v4, 0x80000000, v1
	v_mov_b32_e32 v5, v0
	v_pk_mul_f32 v[4:5], v[74:75], v[4:5]
	s_waitcnt lgkmcnt(6)
	v_lshlrev_b32_e32 v114, 16, v114
	v_lshlrev_b32_e32 v115, 16, v115
	v_pk_fma_f32 v[0:1], v[80:81], v[0:1], v[4:5]
	s_nop 0
	v_pk_add_f32 v[82:83], v[0:1], v[114:115]
	s_nop 0
	v_cvt_pk_bf16_f32 v0, v82, v83
	ds_write_b16 v6, v0 offset:1904
	ds_write_b16_d16_hi v6, v0 offset:2032
	s_cmpk_eq_i32 s39, 0x2200
	s_cbranch_scc0 .LBB0_334
	s_waitcnt lgkmcnt(0)
	s_barrier
	ds_read_b128 v[0:3], v88
	ds_read_b128 v[4:7], v88 offset:64
	s_waitcnt lgkmcnt(1)
	v_mfma_f32_16x16x32_bf16 v[0:3], v[34:37], v[0:3], 0
	ds_read_b128 v[10:13], v88 offset:4416
	s_mov_b64 s[72:73], 0
	s_waitcnt lgkmcnt(1)
	v_mfma_f32_16x16x32_bf16 v[0:3], v[38:41], v[4:7], v[0:3]
	ds_read_b128 v[4:7], v88 offset:128
	s_waitcnt lgkmcnt(0)
	v_mfma_f32_16x16x32_bf16 v[0:3], v[42:45], v[4:7], v[0:3]
	ds_read_b128 v[4:7], v88 offset:192
	s_waitcnt lgkmcnt(0)
	v_mfma_f32_16x16x32_bf16 v[6:9], v[46:49], v[4:7], v[0:3]
	v_or_b32_e32 v5, s38, v84
	s_nop 3
	ds_read_b128 v[0:3], v88 offset:4352
	v_or_b32_e32 v4, s6, v5
	s_waitcnt lgkmcnt(0)
	v_mfma_f32_16x16x32_bf16 v[0:3], v[34:37], v[0:3], 0
	v_mfma_f32_16x16x32_bf16 v[0:3], v[38:41], v[10:13], v[0:3]
	ds_read_b128 v[10:13], v88 offset:4480
	s_waitcnt lgkmcnt(0)
	v_mfma_f32_16x16x32_bf16 v[0:3], v[42:45], v[10:13], v[0:3]
	ds_read_b128 v[10:13], v88 offset:4544
	s_waitcnt lgkmcnt(0)
	v_mfma_f32_16x16x32_bf16 v[0:3], v[46:49], v[10:13], v[0:3]
	v_mad_u64_u32 v[10:11], s[38:39], v4, s45, v[78:79]
	v_mad_u32_u24 v11, s7, v212, v11
	global_load_dwordx2 v[10:11], v[10:11], off offset:2816
	v_or_b32_e32 v4, 16, v4
	s_waitcnt vmcnt(0)
; DI unsigned pk2(float a, float b) { f2_t v = {a, b}; bf2_t r = __builtin_convertvector(v, bf2_t); return __builtin_bit_cast(unsigned, r); }
; DI float bflo(unsigned u) { return __uint_as_float(u << 16); }
; DI float bfhi(unsigned u) { return __uint_as_float(u & 0xffff0000u); }
; DI float gelu_tanh(float x) {
;   const float u = 0.7978845608028654f * (x + 0.044715f * x * x * x);
;   const float e = __expf(2.f * u);
;   const float th = 1.f - 2.f / (e + 1.f);
;   return 0.5f * x * (1.f + th);
; }
; DI void ssm_out_item(const CP& p, int l, int item, char* smem) {
;     ...
; #pragma unroll
;       for (int nb = 0; nb < 2; ++nb) {
;         const int s = sub * 32 + nb * 16 + l16;
;         const u32x2 uu = *(const u32x2*)(p.R + (tok0 + s) * TMW + 1408 + g * 16 + q4 * 4);
;         const float y0 = gelu_tanh(ya[nb][0] + dsk.x * bflo(uu.x));
;         const float y1 = gelu_tanh(ya[nb][1] + dsk.y * bfhi(uu.x));
;         const float y2 = gelu_tanh(ya[nb][2] + dsk.z * bflo(uu.y));
;         const float y3 = gelu_tanh(ya[nb][3] + dsk.w * bfhi(uu.y));
;         u32x2 v;
;         v.x = pk2(y0, y1); v.y = pk2(y2, y3);
;         *(u32x2*)(sY + s * 264 + g * 16 + q4 * 4) = v;
;       }
;       __syncthreads();
	v_lshlrev_b32_e32 v12, 16, v10
	v_and_b32_e32 v13, 0xffff0000, v10
	v_pk_fma_f32 v[6:7], v[50:51], v[12:13], v[6:7]
	s_nop 0
	v_mul_f32_e32 v10, 0x3d372713, v6
	v_mul_f32_e32 v10, v6, v10
	v_fma_f32 v10, v6, v10, v6
	v_mul_f32_e32 v10, 0x3f4c422a, v10
	v_add_f32_e32 v10, v10, v10
	v_mul_f32_e32 v10, 0x3fb8aa3b, v10
	v_exp_f32_e32 v12, v10
	v_mul_f32_e32 v10, 0x3d372713, v7
	v_mul_f32_e32 v10, v7, v10
	v_fma_f32 v10, v7, v10, v7
	v_mul_f32_e32 v10, 0x3f4c422a, v10
	v_add_f32_e32 v10, v10, v10
	v_mul_f32_e32 v10, 0x3fb8aa3b, v10
	v_exp_f32_e32 v13, v10
	v_pk_mul_f32 v[6:7], v[6:7], 0.5 op_sel_hi:[1,0]
	v_pk_add_f32 v[12:13], v[12:13], 1.0 op_sel_hi:[1,0]
	s_nop 0
	v_div_scale_f32 v10, s[38:39], v13, v13, 2.0
	v_rcp_f32_e32 v14, v10
	s_nop 0
	v_fma_f32 v15, -v10, v14, 1.0
	v_fmac_f32_e32 v14, v15, v14
	v_div_scale_f32 v15, vcc, 2.0, v13, 2.0
	v_mul_f32_e32 v90, v15, v14
	v_fma_f32 v91, -v10, v90, v15
	v_fmac_f32_e32 v90, v91, v14
	v_fma_f32 v10, -v10, v90, v15
	v_div_fmas_f32 v10, v10, v14, v90
	v_div_fixup_f32 v13, v10, v13, 2.0
	v_div_scale_f32 v10, s[38:39], v12, v12, 2.0
	v_rcp_f32_e32 v14, v10
	s_nop 0
	v_fma_f32 v15, -v10, v14, 1.0
	v_fmac_f32_e32 v14, v15, v14
	v_div_scale_f32 v15, vcc, 2.0, v12, 2.0
	v_mul_f32_e32 v90, v15, v14
	v_fma_f32 v91, -v10, v90, v15
	v_fmac_f32_e32 v90, v91, v14
	v_fma_f32 v10, -v10, v90, v15
	v_div_fmas_f32 v10, v10, v14, v90
	v_div_fixup_f32 v12, v10, v12, 2.0
	v_lshlrev_b32_e32 v10, 16, v11
	v_and_b32_e32 v11, 0xffff0000, v11
	v_pk_fma_f32 v[8:9], v[52:53], v[10:11], v[8:9]
	v_pk_add_f32 v[12:13], v[12:13], 1.0 op_sel_hi:[1,0] neg_lo:[1,0] neg_hi:[1,0]
	v_mul_f32_e32 v10, 0x3d372713, v8
	v_mul_f32_e32 v11, 0x3d372713, v9
	v_mul_f32_e32 v10, v8, v10
	v_mul_f32_e32 v11, v9, v11
	v_fma_f32 v10, v8, v10, v8
	v_fma_f32 v11, v9, v11, v9
	v_mul_f32_e32 v10, 0x3f4c422a, v10
	v_mul_f32_e32 v11, 0x3f4c422a, v11
	v_add_f32_e32 v10, v10, v10
	v_add_f32_e32 v11, v11, v11
	v_mul_f32_e32 v10, 0x3fb8aa3b, v10
	v_mul_f32_e32 v11, 0x3fb8aa3b, v11
	v_exp_f32_e32 v10, v10
	v_exp_f32_e32 v11, v11
	v_pk_add_f32 v[12:13], v[12:13], 1.0 op_sel_hi:[1,0]
	v_pk_mul_f32 v[8:9], v[8:9], 0.5 op_sel_hi:[1,0]
	v_pk_mul_f32 v[6:7], v[6:7], v[12:13]
	v_pk_add_f32 v[10:11], v[10:11], 1.0 op_sel_hi:[1,0]
	s_nop 0
	v_div_scale_f32 v12, s[38:39], v11, v11, 2.0
	v_rcp_f32_e32 v13, v12
	s_nop 0
	v_fma_f32 v14, -v12, v13, 1.0
	v_fmac_f32_e32 v13, v14, v13
	v_div_scale_f32 v14, vcc, 2.0, v11, 2.0
	v_mul_f32_e32 v15, v14, v13
	v_fma_f32 v90, -v12, v15, v14
	v_fmac_f32_e32 v15, v90, v13
	v_fma_f32 v12, -v12, v15, v14
	v_div_fmas_f32 v12, v12, v13, v15
	v_div_fixup_f32 v11, v12, v11, 2.0
	v_div_scale_f32 v12, s[38:39], v10, v10, 2.0
	v_rcp_f32_e32 v13, v12
	s_nop 0
	v_fma_f32 v14, -v12, v13, 1.0
	v_fmac_f32_e32 v13, v14, v13
	v_div_scale_f32 v14, vcc, 2.0, v10, 2.0
	v_mul_f32_e32 v15, v14, v13
	v_fma_f32 v90, -v12, v15, v14
	v_fmac_f32_e32 v15, v90, v13
	v_fma_f32 v12, -v12, v15, v14
	v_div_fmas_f32 v12, v12, v13, v15
	v_div_fixup_f32 v10, v12, v10, 2.0
	v_pk_add_f32 v[10:11], v[10:11], 1.0 op_sel_hi:[1,0] neg_lo:[1,0] neg_hi:[1,0]
	s_nop 0
	v_pk_add_f32 v[10:11], v[10:11], 1.0 op_sel_hi:[1,0]
	s_nop 0
	v_pk_mul_f32 v[8:9], v[8:9], v[10:11]
	v_cvt_pk_bf16_f32 v10, v6, v7
	v_mad_u32_u24 v6, v5, s88, v89
	v_mad_u64_u32 v[4:5], s[38:39], v4, s45, v[78:79]
	v_mad_u32_u24 v5, s7, v212, v5
	global_load_dwordx2 v[4:5], v[4:5], off offset:2816
	v_cvt_pk_bf16_f32 v11, v8, v9
	ds_write_b64 v6, v[10:11]
	s_waitcnt vmcnt(0)
	v_lshlrev_b32_e32 v8, 16, v4
	v_and_b32_e32 v9, 0xffff0000, v4
	v_pk_fma_f32 v[0:1], v[50:51], v[8:9], v[0:1]
	s_nop 0
	v_mul_f32_e32 v4, 0x3d372713, v0
	v_mul_f32_e32 v4, v0, v4
	v_fma_f32 v4, v0, v4, v0
	v_mul_f32_e32 v4, 0x3f4c422a, v4
	v_add_f32_e32 v4, v4, v4
	v_mul_f32_e32 v4, 0x3fb8aa3b, v4
	v_exp_f32_e32 v8, v4
	v_mul_f32_e32 v4, 0x3d372713, v1
	v_mul_f32_e32 v4, v1, v4
	v_fma_f32 v4, v1, v4, v1
	v_mul_f32_e32 v4, 0x3f4c422a, v4
	v_add_f32_e32 v4, v4, v4
	v_mul_f32_e32 v4, 0x3fb8aa3b, v4
	v_exp_f32_e32 v9, v4
	v_pk_mul_f32 v[0:1], v[0:1], 0.5 op_sel_hi:[1,0]
	v_pk_add_f32 v[8:9], v[8:9], 1.0 op_sel_hi:[1,0]
	s_nop 0
	v_div_scale_f32 v4, s[38:39], v9, v9, 2.0
	v_rcp_f32_e32 v7, v4
	s_nop 0
	v_fma_f32 v10, -v4, v7, 1.0
	v_fmac_f32_e32 v7, v10, v7
	v_div_scale_f32 v10, vcc, 2.0, v9, 2.0
	v_mul_f32_e32 v11, v10, v7
	v_fma_f32 v12, -v4, v11, v10
	v_fmac_f32_e32 v11, v12, v7
	v_fma_f32 v4, -v4, v11, v10
	v_div_fmas_f32 v4, v4, v7, v11
	v_div_fixup_f32 v9, v4, v9, 2.0
	v_div_scale_f32 v4, s[38:39], v8, v8, 2.0
	v_rcp_f32_e32 v7, v4
	s_nop 0
	v_fma_f32 v10, -v4, v7, 1.0
	v_fmac_f32_e32 v7, v10, v7
	v_div_scale_f32 v10, vcc, 2.0, v8, 2.0
	v_mul_f32_e32 v11, v10, v7
	v_fma_f32 v12, -v4, v11, v10
	v_fmac_f32_e32 v11, v12, v7
	v_fma_f32 v4, -v4, v11, v10
	v_div_fmas_f32 v4, v4, v7, v11
	v_div_fixup_f32 v8, v4, v8, 2.0
	v_lshlrev_b32_e32 v4, 16, v5
	v_and_b32_e32 v5, 0xffff0000, v5
	v_pk_fma_f32 v[2:3], v[52:53], v[4:5], v[2:3]
	v_pk_add_f32 v[8:9], v[8:9], 1.0 op_sel_hi:[1,0] neg_lo:[1,0] neg_hi:[1,0]
	v_mul_f32_e32 v4, 0x3d372713, v2
	v_mul_f32_e32 v5, 0x3d372713, v3
	v_mul_f32_e32 v4, v2, v4
	v_mul_f32_e32 v5, v3, v5
	v_fma_f32 v4, v2, v4, v2
	v_fma_f32 v5, v3, v5, v3
	v_mul_f32_e32 v4, 0x3f4c422a, v4
	v_mul_f32_e32 v5, 0x3f4c422a, v5
	v_add_f32_e32 v4, v4, v4
	v_add_f32_e32 v5, v5, v5
	v_mul_f32_e32 v4, 0x3fb8aa3b, v4
	v_mul_f32_e32 v5, 0x3fb8aa3b, v5
	v_exp_f32_e32 v4, v4
	v_exp_f32_e32 v5, v5
	v_pk_add_f32 v[8:9], v[8:9], 1.0 op_sel_hi:[1,0]
	v_pk_mul_f32 v[2:3], v[2:3], 0.5 op_sel_hi:[1,0]
	v_pk_mul_f32 v[0:1], v[0:1], v[8:9]
	v_pk_add_f32 v[4:5], v[4:5], 1.0 op_sel_hi:[1,0]
	v_cvt_pk_bf16_f32 v0, v0, v1
	v_div_scale_f32 v7, s[38:39], v5, v5, 2.0
	v_rcp_f32_e32 v8, v7
	s_nop 0
	v_fma_f32 v9, -v7, v8, 1.0
	v_fmac_f32_e32 v8, v9, v8
	v_div_scale_f32 v9, vcc, 2.0, v5, 2.0
	v_mul_f32_e32 v10, v9, v8
	v_fma_f32 v11, -v7, v10, v9
	v_fmac_f32_e32 v10, v11, v8
	v_fma_f32 v7, -v7, v10, v9
	v_div_fmas_f32 v7, v7, v8, v10
	v_div_fixup_f32 v5, v7, v5, 2.0
	v_div_scale_f32 v7, s[38:39], v4, v4, 2.0
	v_rcp_f32_e32 v8, v7
	s_mov_b32 s38, 32
	v_fma_f32 v9, -v7, v8, 1.0
	v_fmac_f32_e32 v8, v9, v8
	v_div_scale_f32 v9, vcc, 2.0, v4, 2.0
	v_mul_f32_e32 v10, v9, v8
	v_fma_f32 v11, -v7, v10, v9
	v_fmac_f32_e32 v10, v11, v8
	v_fma_f32 v7, -v7, v10, v9
	v_div_fmas_f32 v7, v7, v8, v10
	v_div_fixup_f32 v4, v7, v4, 2.0
	v_pk_add_f32 v[4:5], v[4:5], 1.0 op_sel_hi:[1,0] neg_lo:[1,0] neg_hi:[1,0]
	s_and_b64 vcc, exec, s[70:71]
	v_pk_add_f32 v[4:5], v[4:5], 1.0 op_sel_hi:[1,0]
	s_nop 0
	v_pk_mul_f32 v[2:3], v[2:3], v[4:5]
	s_nop 0
	v_cvt_pk_bf16_f32 v1, v2, v3
	ds_write_b64 v6, v[0:1] offset:8448
	s_waitcnt lgkmcnt(0)
	s_barrier
; #define MFMA32(a, b, c) __builtin_amdgcn_mfma_f32_32x32x16_bf16((a), (b), (c), 0, 0, 0)
; DI void ssm_out_item(const CP& p, int l, int item, char* smem) {
;     ...
;   const u16* wg = p.wt_glu + (size_t)l * 65536;
; #pragma unroll
;   for (int ks = 0; ks < 16; ++ks) {
;     bf16x8 fa, fb[2];
;     fa = *(const bf16x8*)(wg + (size_t)(w * 32 + l32) * 256 + ks * 16 + hh * 8);
; #pragma unroll
;     for (int i = 0; i < 2; ++i) fb[i] = *(const bf16x8*)(sY + (i * 32 + l32) * 264 + ks * 16 + hh * 8);
; #pragma unroll
;     for (int j = 0; j < 2; ++j) acc[j] = MFMA32(fa, fb[j], acc[j]);
;   }
	s_cbranch_vccz .LBB0_333
	s_mov_b32 s38, 1
	s_mov_b64 s[70:71], 0
	s_and_b64 vcc, exec, s[10:11]
	s_cbranch_vccz .LBB0_332
	v_lshlrev_b32_e32 v37, 5, v59
	v_or_b32_e32 v0, v37, v56
	v_ashrrev_i32_e32 v1, 31, v0
	v_lshlrev_b64 v[0:1], 9, v[0:1]
	v_lshl_add_u64 v[0:1], s[30:31], 0, v[0:1]
	v_lshlrev_b32_e32 v32, 1, v58
	v_lshl_add_u64 v[34:35], v[0:1], 0, v[32:33]
	s_barrier
	global_load_dwordx4 v[100:103], v[34:35], off
	global_load_dwordx4 v[104:107], v[34:35], off offset:32
	global_load_dwordx4 v[108:111], v[34:35], off offset:64
	global_load_dwordx4 v[112:115], v[34:35], off offset:96
	global_load_dwordx4 v[116:119], v[34:35], off offset:128
	global_load_dwordx4 v[120:123], v[34:35], off offset:160
	global_load_dwordx4 v[124:127], v[34:35], off offset:192
	global_load_dwordx4 v[128:131], v[34:35], off offset:224
	global_load_dwordx4 v[132:135], v[34:35], off offset:256
	global_load_dwordx4 v[136:139], v[34:35], off offset:288
	global_load_dwordx4 v[140:143], v[34:35], off offset:320
	global_load_dwordx4 v[144:147], v[34:35], off offset:352
	global_load_dwordx4 v[148:151], v[34:35], off offset:384
	global_load_dwordx4 v[168:171], v[34:35], off offset:416
	global_load_dwordx4 v[172:175], v[34:35], off offset:448
	global_load_dwordx4 v[176:179], v[34:35], off offset:480
	v_add_u32_e32 v4, s44, v32
	v_mad_u32_u24 v50, v56, s88, v4
	v_mad_u32_u24 v32, v56, s88, v213
	v_add_u32_e32 v51, v4, v32
	v_mul_u32_u24_e32 v36, 0x210, v56
	v_cmp_gt_u32_e64 s[4:5], 32, v55
	ds_read_b128 v[180:183], v50
	ds_read_b128 v[184:187], v51
	ds_read_b128 v[188:191], v50 offset:32
	ds_read_b128 v[192:195], v51 offset:32
	s_waitcnt vmcnt(15) lgkmcnt(2)
	v_mfma_f32_32x32x16_bf16 v[16:31], v[100:103], v[180:183], 0
	v_mfma_f32_32x32x16_bf16 v[0:15], v[100:103], v[184:187], 0
	ds_read_b128 v[180:183], v50 offset:64
	ds_read_b128 v[184:187], v51 offset:64
	s_waitcnt vmcnt(14) lgkmcnt(2)
	v_mfma_f32_32x32x16_bf16 v[16:31], v[104:107], v[188:191], v[16:31]
	v_mfma_f32_32x32x16_bf16 v[0:15], v[104:107], v[192:195], v[0:15]
	ds_read_b128 v[188:191], v50 offset:96
	ds_read_b128 v[192:195], v51 offset:96
	s_waitcnt vmcnt(13) lgkmcnt(2)
	v_mfma_f32_32x32x16_bf16 v[16:31], v[108:111], v[180:183], v[16:31]
	v_mfma_f32_32x32x16_bf16 v[0:15], v[108:111], v[184:187], v[0:15]
	ds_read_b128 v[180:183], v50 offset:128
	ds_read_b128 v[184:187], v51 offset:128
	s_waitcnt vmcnt(12) lgkmcnt(2)
	v_mfma_f32_32x32x16_bf16 v[16:31], v[112:115], v[188:191], v[16:31]
	v_mfma_f32_32x32x16_bf16 v[0:15], v[112:115], v[192:195], v[0:15]
	ds_read_b128 v[188:191], v50 offset:160
	ds_read_b128 v[192:195], v51 offset:160
	s_waitcnt vmcnt(11) lgkmcnt(2)
	v_mfma_f32_32x32x16_bf16 v[16:31], v[116:119], v[180:183], v[16:31]
	v_mfma_f32_32x32x16_bf16 v[0:15], v[116:119], v[184:187], v[0:15]
	ds_read_b128 v[180:183], v50 offset:192
	ds_read_b128 v[184:187], v51 offset:192
	s_waitcnt vmcnt(10) lgkmcnt(2)
	v_mfma_f32_32x32x16_bf16 v[16:31], v[120:123], v[188:191], v[16:31]
	v_mfma_f32_32x32x16_bf16 v[0:15], v[120:123], v[192:195], v[0:15]
	ds_read_b128 v[188:191], v50 offset:224
	ds_read_b128 v[192:195], v51 offset:224
	s_waitcnt vmcnt(9) lgkmcnt(2)
	v_mfma_f32_32x32x16_bf16 v[16:31], v[124:127], v[180:183], v[16:31]
	v_mfma_f32_32x32x16_bf16 v[0:15], v[124:127], v[184:187], v[0:15]
	ds_read_b128 v[180:183], v50 offset:256
	ds_read_b128 v[184:187], v51 offset:256
	s_waitcnt vmcnt(8) lgkmcnt(2)
	v_mfma_f32_32x32x16_bf16 v[16:31], v[128:131], v[188:191], v[16:31]
	v_mfma_f32_32x32x16_bf16 v[0:15], v[128:131], v[192:195], v[0:15]
	ds_read_b128 v[188:191], v50 offset:288
	ds_read_b128 v[192:195], v51 offset:288
	s_waitcnt vmcnt(7) lgkmcnt(2)
	v_mfma_f32_32x32x16_bf16 v[16:31], v[132:135], v[180:183], v[16:31]
	v_mfma_f32_32x32x16_bf16 v[0:15], v[132:135], v[184:187], v[0:15]
	ds_read_b128 v[180:183], v50 offset:320
	ds_read_b128 v[184:187], v51 offset:320
	s_waitcnt vmcnt(6) lgkmcnt(2)
	v_mfma_f32_32x32x16_bf16 v[16:31], v[136:139], v[188:191], v[16:31]
	v_mfma_f32_32x32x16_bf16 v[0:15], v[136:139], v[192:195], v[0:15]
	ds_read_b128 v[188:191], v50 offset:352
	ds_read_b128 v[192:195], v51 offset:352
	s_waitcnt vmcnt(5) lgkmcnt(2)
	v_mfma_f32_32x32x16_bf16 v[16:31], v[140:143], v[180:183], v[16:31]
	v_mfma_f32_32x32x16_bf16 v[0:15], v[140:143], v[184:187], v[0:15]
	ds_read_b128 v[180:183], v50 offset:384
	ds_read_b128 v[184:187], v51 offset:384
	s_waitcnt vmcnt(4) lgkmcnt(2)
	v_mfma_f32_32x32x16_bf16 v[16:31], v[144:147], v[188:191], v[16:31]
	v_mfma_f32_32x32x16_bf16 v[0:15], v[144:147], v[192:195], v[0:15]
	ds_read_b128 v[188:191], v50 offset:416
	ds_read_b128 v[192:195], v51 offset:416
	s_waitcnt vmcnt(3) lgkmcnt(2)
	v_mfma_f32_32x32x16_bf16 v[16:31], v[148:151], v[180:183], v[16:31]
	v_mfma_f32_32x32x16_bf16 v[0:15], v[148:151], v[184:187], v[0:15]
	ds_read_b128 v[180:183], v50 offset:448
	ds_read_b128 v[184:187], v51 offset:448
	s_waitcnt vmcnt(2) lgkmcnt(2)
	v_mfma_f32_32x32x16_bf16 v[16:31], v[168:171], v[188:191], v[16:31]
	v_mfma_f32_32x32x16_bf16 v[0:15], v[168:171], v[192:195], v[0:15]
	ds_read_b128 v[188:191], v50 offset:480
	ds_read_b128 v[192:195], v51 offset:480
	s_waitcnt vmcnt(1) lgkmcnt(2)
	v_mfma_f32_32x32x16_bf16 v[16:31], v[172:175], v[180:183], v[16:31]
	v_mfma_f32_32x32x16_bf16 v[0:15], v[172:175], v[184:187], v[0:15]
	s_waitcnt vmcnt(0) lgkmcnt(0)
	v_mfma_f32_32x32x16_bf16 v[16:31], v[176:179], v[188:191], v[16:31]
	v_mfma_f32_32x32x16_bf16 v[0:15], v[176:179], v[192:195], v[0:15]
	v_and_b32_e32 v34, 0x3fffffc0, v54
	v_mov_b32_e32 v35, s7
	v_lshl_or_b32 v40, v57, 2, v37
	v_ashrrev_i32_e32 v41, 31, v40
	v_lshl_add_u64 v[38:39], v[40:41], 2, s[68:69]
	global_load_dwordx4 v[50:53], v[38:39], off
	v_lshl_add_u32 v48, v34, 2, s36
	v_or_b32_e32 v34, s6, v56
	v_lshlrev_b64 v[34:35], 11, v[34:35]
	v_lshl_add_u64 v[44:45], s[66:67], 0, v[34:35]
	v_lshlrev_b32_e32 v34, 1, v40
	v_add3_u32 v46, s44, v36, v34
	ds_read2_b64 v[34:37], v46 offset1:2
	v_lshl_add_u64 v[44:45], v[40:41], 1, v[44:45]
	s_waitcnt vmcnt(0)
; DI unsigned pk2(float a, float b) { f2_t v = {a, b}; bf2_t r = __builtin_convertvector(v, bf2_t); return __builtin_bit_cast(unsigned, r); }
; DI float bflo(unsigned u) { return __uint_as_float(u << 16); }
; DI float bfhi(unsigned u) { return __uint_as_float(u & 0xffff0000u); }
; DI void ssm_out_item(const CP& p, int l, int item, char* smem) {
;     ...
;   const float* bg = p.b_glu + (size_t)l * 256;
; #pragma unroll
;   for (int j = 0; j < 2; ++j) {
;     const int token = j * 32 + l32;
;     float sq = 0.f;
; #pragma unroll
;     for (int blk = 0; blk < 4; ++blk) {
;       const int ch = w * 32 + 8 * blk + 4 * hh;
;       const fl4 bv = *(const fl4*)(bg + ch);
;       const u32x2 yy = *(const u32x2*)(sY + token * 264 + ch);
;       const float g0 = 1.f / (1.f + __expf(-(acc[j][4 * blk] + bv.x)));
;       const float g1 = 1.f / (1.f + __expf(-(acc[j][4 * blk + 1] + bv.y)));
;       const float g2 = 1.f / (1.f + __expf(-(acc[j][4 * blk + 2] + bv.z)));
;       const float g3 = 1.f / (1.f + __expf(-(acc[j][4 * blk + 3] + bv.w)));
;       const float o0 = bflo(yy.x) * g0, o1 = bfhi(yy.x) * g1, o2 = bflo(yy.y) * g2, o3 = bfhi(yy.y) * g3;
;       sq += o0 * o0 + o1 * o1 + o2 * o2 + o3 * o3;
;       u32x2 v;
;       v.x = pk2(o0, o1); v.y = pk2(o2, o3);
;       *(u32x2*)(p.mixed + (tok0 + token) * 1024 + 768 + ch) = v;
;     }
	v_add_f32_e32 v16, v16, v50
	v_add_f32_e32 v17, v17, v51
	v_mul_f32_e32 v16, 0xbfb8aa3b, v16
	v_mul_f32_e32 v17, 0xbfb8aa3b, v17
	v_exp_f32_e32 v16, v16
	v_exp_f32_e32 v17, v17
	v_add_f32_e32 v18, v18, v52
	v_add_f32_e32 v19, v19, v53
	v_mul_f32_e32 v18, 0xbfb8aa3b, v18
	v_pk_add_f32 v[16:17], v[16:17], 1.0 op_sel_hi:[1,0]
	v_mul_f32_e32 v19, 0xbfb8aa3b, v19
	v_div_scale_f32 v42, s[10:11], v17, v17, 1.0
	v_rcp_f32_e32 v43, v42
	v_exp_f32_e32 v18, v18
	v_exp_f32_e32 v19, v19
	v_fma_f32 v47, -v42, v43, 1.0
	v_fmac_f32_e32 v43, v47, v43
	v_div_scale_f32 v47, vcc, 1.0, v17, 1.0
	v_mul_f32_e32 v49, v47, v43
	v_fma_f32 v50, -v42, v49, v47
	v_fmac_f32_e32 v49, v50, v43
	v_fma_f32 v42, -v42, v49, v47
	v_div_fmas_f32 v42, v42, v43, v49
	v_div_fixup_f32 v17, v42, v17, 1.0
	v_div_scale_f32 v42, s[10:11], v16, v16, 1.0
	v_rcp_f32_e32 v43, v42
	v_pk_add_f32 v[18:19], v[18:19], 1.0 op_sel_hi:[1,0]
	v_fma_f32 v47, -v42, v43, 1.0
	v_fmac_f32_e32 v43, v47, v43
	v_div_scale_f32 v47, vcc, 1.0, v16, 1.0
	v_mul_f32_e32 v49, v47, v43
	v_fma_f32 v50, -v42, v49, v47
	v_fmac_f32_e32 v49, v50, v43
	v_fma_f32 v42, -v42, v49, v47
	v_div_fmas_f32 v42, v42, v43, v49
	v_div_fixup_f32 v16, v42, v16, 1.0
	s_waitcnt lgkmcnt(0)
	v_lshlrev_b32_e32 v42, 16, v34
	v_and_b32_e32 v43, 0xffff0000, v34
	v_div_scale_f32 v34, s[10:11], v19, v19, 1.0
	v_pk_mul_f32 v[16:17], v[16:17], v[42:43]
	v_rcp_f32_e32 v42, v34
	s_nop 0
	v_fma_f32 v43, -v34, v42, 1.0
	v_fmac_f32_e32 v42, v43, v42
	v_div_scale_f32 v43, vcc, 1.0, v19, 1.0
	v_mul_f32_e32 v47, v43, v42
	v_fma_f32 v49, -v34, v47, v43
	v_fmac_f32_e32 v47, v49, v42
	v_fma_f32 v34, -v34, v47, v43
	v_div_fmas_f32 v34, v34, v42, v47
	v_div_fixup_f32 v19, v34, v19, 1.0
	v_div_scale_f32 v34, s[10:11], v18, v18, 1.0
	v_rcp_f32_e32 v42, v34
	s_nop 0
	v_fma_f32 v43, -v34, v42, 1.0
	v_fmac_f32_e32 v42, v43, v42
	v_div_scale_f32 v43, vcc, 1.0, v18, 1.0
	v_mul_f32_e32 v47, v43, v42
	v_fma_f32 v49, -v34, v47, v43
	v_fmac_f32_e32 v47, v49, v42
	v_fma_f32 v34, -v34, v47, v43
	v_div_fmas_f32 v34, v34, v42, v47
	v_div_fixup_f32 v18, v34, v18, 1.0
	v_lshlrev_b32_e32 v34, 16, v35
	v_and_b32_e32 v35, 0xffff0000, v35
	v_pk_mul_f32 v[18:19], v[18:19], v[34:35]
	v_pk_mul_f32 v[42:43], v[16:17], v[16:17]
	v_cvt_pk_bf16_f32 v16, v16, v17
	v_cvt_pk_bf16_f32 v17, v18, v19
	global_store_dwordx2 v[44:45], v[16:17], off offset:1536
	v_pk_mul_f32 v[34:35], v[18:19], v[18:19]
	global_load_dwordx4 v[16:19], v[38:39], off offset:32
	s_waitcnt vmcnt(0)
	v_add_f32_e32 v16, v20, v16
	v_add_f32_e32 v17, v21, v17
	v_mul_f32_e32 v16, 0xbfb8aa3b, v16
	v_mul_f32_e32 v17, 0xbfb8aa3b, v17
	v_exp_f32_e32 v16, v16
	v_exp_f32_e32 v17, v17
	v_add_f32_e32 v18, v22, v18
	v_mul_f32_e32 v18, 0xbfb8aa3b, v18
	v_exp_f32_e32 v20, v18
	v_add_f32_e32 v18, v23, v19
	v_mul_f32_e32 v18, 0xbfb8aa3b, v18
	v_pk_add_f32 v[16:17], v[16:17], 1.0 op_sel_hi:[1,0]
	v_exp_f32_e32 v21, v18
	v_div_scale_f32 v18, s[10:11], v17, v17, 1.0
	v_rcp_f32_e32 v19, v18
	v_pk_add_f32 v[20:21], v[20:21], 1.0 op_sel_hi:[1,0]
	v_fma_f32 v22, -v18, v19, 1.0
	v_fmac_f32_e32 v19, v22, v19
	v_div_scale_f32 v22, vcc, 1.0, v17, 1.0
	v_mul_f32_e32 v23, v22, v19
	v_fma_f32 v47, -v18, v23, v22
	v_fmac_f32_e32 v23, v47, v19
	v_fma_f32 v18, -v18, v23, v22
	v_div_fmas_f32 v18, v18, v19, v23
	v_div_fixup_f32 v23, v18, v17, 1.0
	v_div_scale_f32 v17, s[10:11], v16, v16, 1.0
	v_rcp_f32_e32 v18, v17
	s_nop 0
	v_fma_f32 v19, -v17, v18, 1.0
	v_fmac_f32_e32 v18, v19, v18
	v_div_scale_f32 v19, vcc, 1.0, v16, 1.0
	v_mul_f32_e32 v22, v19, v18
	v_fma_f32 v47, -v17, v22, v19
	v_fmac_f32_e32 v22, v47, v18
	v_fma_f32 v17, -v17, v22, v19
	v_div_fmas_f32 v17, v17, v18, v22
	v_div_fixup_f32 v22, v17, v16, 1.0
	ds_read2_b64 v[16:19], v46 offset0:4 offset1:6
	v_lshlrev_b32_e32 v46, 16, v36
	v_and_b32_e32 v47, 0xffff0000, v36
	v_pk_mul_f32 v[46:47], v[22:23], v[46:47]
	v_div_scale_f32 v22, s[10:11], v21, v21, 1.0
	v_rcp_f32_e32 v23, v22
	s_nop 0
	v_fma_f32 v36, -v22, v23, 1.0
	v_fmac_f32_e32 v23, v36, v23
	v_div_scale_f32 v36, vcc, 1.0, v21, 1.0
	v_mul_f32_e32 v49, v36, v23
	v_fma_f32 v50, -v22, v49, v36
	v_fmac_f32_e32 v49, v50, v23
	v_fma_f32 v22, -v22, v49, v36
	v_div_fmas_f32 v22, v22, v23, v49
	v_div_fixup_f32 v21, v22, v21, 1.0
	v_div_scale_f32 v22, s[10:11], v20, v20, 1.0
	v_rcp_f32_e32 v23, v22
	s_nop 0
	v_fma_f32 v36, -v22, v23, 1.0
	v_fmac_f32_e32 v23, v36, v23
	v_div_scale_f32 v36, vcc, 1.0, v20, 1.0
	v_mul_f32_e32 v49, v36, v23
	v_fma_f32 v50, -v22, v49, v36
	v_fmac_f32_e32 v49, v50, v23
	v_fma_f32 v22, -v22, v49, v36
	v_div_fmas_f32 v22, v22, v23, v49
	v_div_fixup_f32 v20, v22, v20, 1.0
	v_lshlrev_b32_e32 v22, 16, v37
	v_and_b32_e32 v23, 0xffff0000, v37
	v_pk_mul_f32 v[36:37], v[20:21], v[22:23]
	v_pk_mul_f32 v[22:23], v[46:47], v[46:47]
	v_cvt_pk_bf16_f32 v46, v46, v47
	v_cvt_pk_bf16_f32 v47, v36, v37
	global_store_dwordx2 v[44:45], v[46:47], off offset:1552
	global_load_dwordx4 v[50:53], v[38:39], off offset:64
	v_pk_mul_f32 v[20:21], v[36:37], v[36:37]
	v_add_f32_e32 v22, v22, v23
	v_add_f32_e32 v20, v20, v22
	v_add_f32_e32 v20, v21, v20
	s_waitcnt vmcnt(0)
; DI unsigned pk2(float a, float b) { f2_t v = {a, b}; bf2_t r = __builtin_convertvector(v, bf2_t); return __builtin_bit_cast(unsigned, r); }
; DI float bflo(unsigned u) { return __uint_as_float(u << 16); }
; DI float bfhi(unsigned u) { return __uint_as_float(u & 0xffff0000u); }
; DI float shx32(float v) { return shx(v, get_tid() & 63, 32); }
; DI void ssm_out_item(const CP& p, int l, int item, char* smem) {
;     ...
; #pragma unroll
;     for (int blk = 0; blk < 4; ++blk) {
;       const int ch = w * 32 + 8 * blk + 4 * hh;
;       const fl4 bv = *(const fl4*)(bg + ch);
;       const u32x2 yy = *(const u32x2*)(sY + token * 264 + ch);
;       const float g0 = 1.f / (1.f + __expf(-(acc[j][4 * blk] + bv.x)));
;       const float g1 = 1.f / (1.f + __expf(-(acc[j][4 * blk + 1] + bv.y)));
;       const float g2 = 1.f / (1.f + __expf(-(acc[j][4 * blk + 2] + bv.z)));
;       const float g3 = 1.f / (1.f + __expf(-(acc[j][4 * blk + 3] + bv.w)));
;       const float o0 = bflo(yy.x) * g0, o1 = bfhi(yy.x) * g1, o2 = bflo(yy.y) * g2, o3 = bfhi(yy.y) * g3;
;       sq += o0 * o0 + o1 * o1 + o2 * o2 + o3 * o3;
;       u32x2 v;
;       v.x = pk2(o0, o1); v.y = pk2(o2, o3);
;       *(u32x2*)(p.mixed + (tok0 + token) * 1024 + 768 + ch) = v;
;     }
;     sq += shx32(sq);
;     if (hh == 0) sSS[w * 64 + token] = sq;
	v_add_f32_e32 v24, v24, v50
	v_add_f32_e32 v25, v25, v51
	v_mul_f32_e32 v24, 0xbfb8aa3b, v24
	v_mul_f32_e32 v25, 0xbfb8aa3b, v25
	v_exp_f32_e32 v24, v24
	v_exp_f32_e32 v25, v25
	v_add_f32_e32 v26, v26, v52
	v_add_f32_e32 v27, v27, v53
	v_mul_f32_e32 v26, 0xbfb8aa3b, v26
	v_pk_add_f32 v[24:25], v[24:25], 1.0 op_sel_hi:[1,0]
	v_mul_f32_e32 v27, 0xbfb8aa3b, v27
	v_div_scale_f32 v36, s[10:11], v25, v25, 1.0
	v_rcp_f32_e32 v37, v36
	v_exp_f32_e32 v26, v26
	v_exp_f32_e32 v27, v27
	v_fma_f32 v46, -v36, v37, 1.0
	v_fmac_f32_e32 v37, v46, v37
	v_div_scale_f32 v46, vcc, 1.0, v25, 1.0
	v_mul_f32_e32 v47, v46, v37
	v_fma_f32 v49, -v36, v47, v46
	v_fmac_f32_e32 v47, v49, v37
	v_fma_f32 v36, -v36, v47, v46
	v_div_fmas_f32 v36, v36, v37, v47
	v_div_fixup_f32 v25, v36, v25, 1.0
	v_div_scale_f32 v36, s[10:11], v24, v24, 1.0
	v_rcp_f32_e32 v37, v36
	v_pk_add_f32 v[26:27], v[26:27], 1.0 op_sel_hi:[1,0]
	v_fma_f32 v46, -v36, v37, 1.0
	v_fmac_f32_e32 v37, v46, v37
	v_div_scale_f32 v46, vcc, 1.0, v24, 1.0
	v_mul_f32_e32 v47, v46, v37
	v_fma_f32 v49, -v36, v47, v46
	v_fmac_f32_e32 v47, v49, v37
	v_fma_f32 v36, -v36, v47, v46
	v_div_fmas_f32 v36, v36, v37, v47
	v_div_fixup_f32 v24, v36, v24, 1.0
	s_waitcnt lgkmcnt(0)
	v_lshlrev_b32_e32 v36, 16, v16
	v_and_b32_e32 v37, 0xffff0000, v16
	v_div_scale_f32 v16, s[10:11], v27, v27, 1.0
	v_pk_mul_f32 v[24:25], v[24:25], v[36:37]
	v_rcp_f32_e32 v36, v16
	s_nop 0
	v_fma_f32 v37, -v16, v36, 1.0
	v_fmac_f32_e32 v36, v37, v36
	v_div_scale_f32 v37, vcc, 1.0, v27, 1.0
	v_mul_f32_e32 v46, v37, v36
	v_fma_f32 v47, -v16, v46, v37
	v_fmac_f32_e32 v46, v47, v36
	v_fma_f32 v16, -v16, v46, v37
	v_div_fmas_f32 v16, v16, v36, v46
	v_div_fixup_f32 v27, v16, v27, 1.0
	v_div_scale_f32 v16, s[10:11], v26, v26, 1.0
	v_rcp_f32_e32 v36, v16
	s_nop 0
	v_fma_f32 v37, -v16, v36, 1.0
	v_fmac_f32_e32 v36, v37, v36
	v_div_scale_f32 v37, vcc, 1.0, v26, 1.0
	v_mul_f32_e32 v46, v37, v36
	v_fma_f32 v47, -v16, v46, v37
	v_fmac_f32_e32 v46, v47, v36
	v_fma_f32 v16, -v16, v46, v37
	v_div_fmas_f32 v16, v16, v36, v46
	v_div_fixup_f32 v26, v16, v26, 1.0
	v_lshlrev_b32_e32 v16, 16, v17
	v_and_b32_e32 v17, 0xffff0000, v17
	v_pk_mul_f32 v[36:37], v[26:27], v[16:17]
	v_pk_mul_f32 v[26:27], v[24:25], v[24:25]
	v_cvt_pk_bf16_f32 v24, v24, v25
	v_cvt_pk_bf16_f32 v25, v36, v37
	global_store_dwordx2 v[44:45], v[24:25], off offset:1568
	global_load_dwordx4 v[50:53], v[38:39], off offset:96
	v_pk_mul_f32 v[16:17], v[36:37], v[36:37]
	v_add_f32_e32 v21, v26, v27
	v_add_f32_e32 v16, v16, v21
	v_add_f32_e32 v16, v17, v16
	v_lshl_add_u32 v26, v56, 2, v48
	s_waitcnt vmcnt(0)
	v_add_f32_e32 v24, v28, v50
	v_add_f32_e32 v25, v29, v51
	v_mul_f32_e32 v24, 0xbfb8aa3b, v24
	v_mul_f32_e32 v25, 0xbfb8aa3b, v25
	v_exp_f32_e32 v24, v24
	v_exp_f32_e32 v25, v25
	v_add_f32_e32 v28, v30, v52
	v_add_f32_e32 v29, v31, v53
	v_mul_f32_e32 v28, 0xbfb8aa3b, v28
	v_pk_add_f32 v[24:25], v[24:25], 1.0 op_sel_hi:[1,0]
	v_mul_f32_e32 v29, 0xbfb8aa3b, v29
	v_div_scale_f32 v30, s[10:11], v25, v25, 1.0
	v_rcp_f32_e32 v31, v30
	v_exp_f32_e32 v28, v28
	v_exp_f32_e32 v29, v29
	v_fma_f32 v36, -v30, v31, 1.0
	v_fmac_f32_e32 v31, v36, v31
	v_div_scale_f32 v36, vcc, 1.0, v25, 1.0
	v_mul_f32_e32 v37, v36, v31
	v_fma_f32 v46, -v30, v37, v36
	v_fmac_f32_e32 v37, v46, v31
	v_fma_f32 v30, -v30, v37, v36
	v_div_fmas_f32 v30, v30, v31, v37
	v_div_fixup_f32 v25, v30, v25, 1.0
	v_div_scale_f32 v30, s[10:11], v24, v24, 1.0
	v_rcp_f32_e32 v31, v30
	v_pk_add_f32 v[28:29], v[28:29], 1.0 op_sel_hi:[1,0]
	v_fma_f32 v36, -v30, v31, 1.0
	v_fmac_f32_e32 v31, v36, v31
	v_div_scale_f32 v36, vcc, 1.0, v24, 1.0
	v_mul_f32_e32 v37, v36, v31
	v_fma_f32 v46, -v30, v37, v36
	v_fmac_f32_e32 v37, v46, v31
	v_fma_f32 v30, -v30, v37, v36
	v_div_fmas_f32 v30, v30, v31, v37
	v_div_fixup_f32 v24, v30, v24, 1.0
	v_lshlrev_b32_e32 v30, 16, v18
	v_and_b32_e32 v31, 0xffff0000, v18
	v_div_scale_f32 v18, s[10:11], v29, v29, 1.0
	v_pk_mul_f32 v[24:25], v[24:25], v[30:31]
	v_rcp_f32_e32 v30, v18
	s_nop 0
	v_fma_f32 v31, -v18, v30, 1.0
	v_fmac_f32_e32 v30, v31, v30
	v_div_scale_f32 v31, vcc, 1.0, v29, 1.0
	v_mul_f32_e32 v36, v31, v30
	v_fma_f32 v37, -v18, v36, v31
	v_fmac_f32_e32 v36, v37, v30
	v_fma_f32 v18, -v18, v36, v31
	v_div_fmas_f32 v18, v18, v30, v36
	v_div_fixup_f32 v29, v18, v29, 1.0
	v_div_scale_f32 v18, s[10:11], v28, v28, 1.0
	v_rcp_f32_e32 v30, v18
	s_nop 0
	v_fma_f32 v31, -v18, v30, 1.0
	v_fmac_f32_e32 v30, v31, v30
	v_div_scale_f32 v31, vcc, 1.0, v28, 1.0
	v_mul_f32_e32 v36, v31, v30
	v_fma_f32 v37, -v18, v36, v31
	v_fmac_f32_e32 v36, v37, v30
	v_fma_f32 v18, -v18, v36, v31
	v_div_fmas_f32 v18, v18, v30, v36
	v_div_fixup_f32 v28, v18, v28, 1.0
	v_lshlrev_b32_e32 v18, 16, v19
	v_and_b32_e32 v19, 0xffff0000, v19
	v_add_f32_e32 v36, v42, v43
	v_pk_mul_f32 v[18:19], v[28:29], v[18:19]
	v_pk_mul_f32 v[28:29], v[24:25], v[24:25]
	v_add_f32_e32 v34, v34, v36
	v_pk_mul_f32 v[30:31], v[18:19], v[18:19]
	v_add_f32_e32 v34, v35, v34
	v_add_f32_e32 v17, v28, v29
	v_add_f32_e32 v20, v34, v20
	v_add_f32_e32 v17, v30, v17
	v_add_f32_e32 v16, v20, v16
	v_add_f32_e32 v17, v31, v17
	v_add_f32_e32 v16, v16, v17
	v_cvt_pk_bf16_f32 v20, v24, v25
	v_cvt_pk_bf16_f32 v21, v18, v19
	v_mov_b32_e32 v17, v202
	global_store_dwordx2 v[44:45], v[20:21], off offset:1584
	s_nop 0
	v_lshlrev_b32_e32 v17, 2, v17
	v_bitop3_b32 v17, v17, s84, v211 bitop3:0x6c
	ds_bpermute_b32 v17, v17, v16
	s_and_saveexec_b64 s[10:11], s[4:5]
	s_cbranch_execz .LBB0_339
	s_waitcnt lgkmcnt(0)
	v_add_f32_e32 v16, v16, v17
	ds_write_b32 v26, v16

; #define MFMA32(a, b, c) __builtin_amdgcn_mfma_f32_32x32x16_bf16((a), (b), (c), 0, 0, 0)
; DI float ex2(float x) { return __builtin_amdgcn_exp2f(x); }
; DI float shx32(float v) { return shx(v, get_tid() & 63, 32); }
; template <int MODE>
; DI void attn_item(const CP& p, int l, int b, int head, int qt, char* smem) {
;     ...
; #pragma unroll
;       for (int rb = 0; rb < 2; ++rb)
; #pragma unroll
;         for (int ks = 0; ks < 4; ++ks) {
;           bf16x8 a = *(const bf16x8*)(cK + (rb * 32 + l32) * 72 + ks * 16 + hh * 8);
;           s[rb] = MFMA32(a, qf[ks], s[rb]);
;         }
;     ...
;       } else if (MODE == 2) {
;         float mx = -INFINITY;
; #pragma unroll
;         for (int rb = 0; rb < 2; ++rb)
; #pragma unroll
;           for (int r = 0; r < 16; r += 2) mx = fmaxf(mx, fmaxf(s[rb][r], s[rb][r + 1]));
;         mx = fmaxf(mx, shx32(mx));
;         const float d = first ? mx : (mx > 8.f ? mx : 0.f);
;         float sum = 0.f;
;         if (__builtin_amdgcn_ballot_w64(d != 0.f) == 0ull) {
; #pragma unroll
;           for (int rb = 0; rb < 2; ++rb)
; #pragma unroll
;             for (int r = 0; r < 16; ++r) { const float e = ex2(s[rb][r]); s[rb][r] = e; sum += e; }
;           sum += shx32(sum);
;           lsum += sum;
;         } else {
;           const float corr = ex2(-d);
;           m += d;
; #pragma unroll
;           for (int rb = 0; rb < 2; ++rb)
; #pragma unroll
;             for (int r = 0; r < 16; ++r) { const float e = ex2(s[rb][r] - d); s[rb][r] = e; sum += e; }
;           sum += shx32(sum);
;           lsum = lsum * corr + sum;
; #pragma unroll
;           for (int r = 0; r < 16; ++r) { o[0][r] *= corr; o[1][r] *= corr; }
;         }
.Lfx_s:
	ds_read_b128 v[216:219], v195 offset:18432
	ds_read_b128 v[220:223], v195 offset:18464
	ds_read_b128 v[224:227], v195 offset:18496
	ds_read_b128 v[228:231], v195 offset:18528
	s_waitcnt lgkmcnt(8)
	v_mfma_f32_32x32x16_bf16 v[66:81], v[98:101], v[130:133], v[66:81]
	v_mfma_f32_32x32x16_bf16 v[66:81], v[102:105], v[134:137], v[66:81]
	v_mfma_f32_32x32x16_bf16 v[66:81], v[106:109], v[138:141], v[66:81]
	v_mfma_f32_32x32x16_bf16 v[66:81], v[110:113], v[142:145], v[66:81]
	ds_read_b128 v[232:235], v195 offset:23040
	ds_read_b128 v[236:239], v195 offset:23072
	ds_read_b128 v[240:243], v195 offset:23104
	ds_read_b128 v[244:247], v195 offset:23136
	s_waitcnt lgkmcnt(8)
	v_mfma_f32_32x32x16_bf16 v[82:97], v[114:117], v[130:133], v[82:97]
	v_mfma_f32_32x32x16_bf16 v[82:97], v[118:121], v[134:137], v[82:97]
	v_mfma_f32_32x32x16_bf16 v[82:97], v[122:125], v[138:141], v[82:97]
	v_mfma_f32_32x32x16_bf16 v[82:97], v[126:129], v[142:145], v[82:97]
	s_mov_b32 s8, 0x41000000
	s_nop 1
	v_max3_f32 v0, v66, v67, v68
	v_max3_f32 v1, v74, v75, v76
	v_max3_f32 v0, v0, v69, v70
	v_max3_f32 v1, v1, v77, v78
	v_max3_f32 v0, v0, v71, v72
	v_max3_f32 v1, v1, v79, v80
	v_max3_f32 v0, v0, v73, v81
	s_nop 1
	v_max3_f32 v2, v82, v83, v84
	v_max3_f32 v3, v90, v91, v92
	v_max3_f32 v2, v2, v85, v86
	v_max3_f32 v3, v3, v93, v94
	v_max3_f32 v2, v2, v87, v88
	v_max3_f32 v3, v3, v95, v96
	v_max3_f32 v2, v2, v89, v97
	v_max3_f32 v0, v0, v1, v2
	v_max_f32_e32 v0, v0, v3
	v_mov_b32_e32 v1, v0
	s_nop 1
	v_permlane32_swap_b32_e32 v0, v1
	v_max_f32_e32 v0, v0, v1
	v_cmp_lt_f32_e32 vcc, s8, v0
	s_or_b64 vcc, s[72:73], vcc
	s_nop 1
	v_cndmask_b32_e32 v179, 0, v0, vcc
	v_cmp_neq_f32_e32 vcc, 0, v179
	s_cbranch_vccz .Lfx_norescale
	v_sub_f32_e32 v0, v66, v179
	v_exp_f32_e32 v0, v0
	v_sub_f32_e32 v1, v67, v179
	v_exp_f32_e32 v1, v1
	v_sub_f32_e32 v2, v68, v179
	v_exp_f32_e32 v2, v2
	v_sub_f32_e32 v3, v69, v179
	v_exp_f32_e32 v3, v3
	v_add_f32_e32 v4, 0, v0
	v_add_f32_e32 v4, v1, v4
	v_add_f32_e32 v4, v2, v4
	v_add_f32_e32 v8, v3, v4
	v_sub_f32_e32 v4, v70, v179
	v_exp_f32_e32 v4, v4
	v_sub_f32_e32 v5, v71, v179
	v_exp_f32_e32 v5, v5
	v_sub_f32_e32 v6, v72, v179
	v_exp_f32_e32 v6, v6
	v_sub_f32_e32 v7, v73, v179
	v_exp_f32_e32 v7, v7
	v_add_f32_e32 v8, v4, v8
	v_add_f32_e32 v8, v5, v8
	v_add_f32_e32 v8, v6, v8
	v_add_f32_e32 v12, v7, v8
	v_sub_f32_e32 v8, v74, v179
	v_exp_f32_e32 v8, v8
	v_sub_f32_e32 v9, v75, v179
	v_exp_f32_e32 v9, v9
	v_sub_f32_e32 v10, v76, v179
	v_exp_f32_e32 v10, v10
	v_sub_f32_e32 v11, v77, v179
	v_exp_f32_e32 v11, v11
	v_add_f32_e32 v12, v8, v12
	v_add_f32_e32 v12, v9, v12
	v_add_f32_e32 v12, v10, v12
	v_add_f32_e32 v16, v11, v12
	v_sub_f32_e32 v12, v78, v179
	v_exp_f32_e32 v12, v12
	v_sub_f32_e32 v13, v79, v179
	v_exp_f32_e32 v13, v13
	v_sub_f32_e32 v14, v80, v179
	v_exp_f32_e32 v14, v14
	v_sub_f32_e32 v15, v81, v179
	v_exp_f32_e32 v15, v15
	v_add_f32_e32 v16, v12, v16
	v_add_f32_e32 v16, v13, v16
	v_add_f32_e32 v16, v14, v16
	v_add_f32_e32 v20, v15, v16
	v_sub_f32_e32 v16, v82, v179
	v_exp_f32_e32 v16, v16
	v_sub_f32_e32 v17, v83, v179
	v_exp_f32_e32 v17, v17
	v_sub_f32_e32 v18, v84, v179
	v_exp_f32_e32 v18, v18
	v_sub_f32_e32 v19, v85, v179
	v_exp_f32_e32 v19, v19
	v_add_f32_e32 v20, v16, v20
	v_add_f32_e32 v20, v17, v20
	v_add_f32_e32 v20, v18, v20
	v_add_f32_e32 v24, v19, v20
	v_sub_f32_e32 v20, v86, v179
	v_exp_f32_e32 v20, v20
	v_sub_f32_e32 v21, v87, v179
	v_exp_f32_e32 v21, v21
	v_sub_f32_e32 v22, v88, v179
	v_exp_f32_e32 v22, v22
	v_sub_f32_e32 v23, v89, v179
	v_exp_f32_e32 v23, v23
	v_add_f32_e32 v24, v20, v24
	v_add_f32_e32 v24, v21, v24
	v_add_f32_e32 v24, v22, v24
	v_add_f32_e32 v28, v23, v24
	v_sub_f32_e32 v24, v90, v179
	v_exp_f32_e32 v24, v24
	v_sub_f32_e32 v25, v91, v179
	v_exp_f32_e32 v25, v25
	v_sub_f32_e32 v26, v92, v179
	v_exp_f32_e32 v26, v26
	v_sub_f32_e32 v27, v93, v179
	v_exp_f32_e32 v27, v27
	v_add_f32_e32 v28, v24, v28
	v_add_f32_e32 v28, v25, v28
	v_add_f32_e32 v28, v26, v28
	v_add_f32_e32 v98, v27, v28
	v_sub_f32_e32 v28, v94, v179
	v_exp_f32_e32 v28, v28
	v_sub_f32_e32 v29, v95, v179
	v_exp_f32_e32 v29, v29
	v_sub_f32_e32 v30, v96, v179
	v_exp_f32_e32 v30, v30
	v_sub_f32_e32 v31, v97, v179
	v_exp_f32_e32 v31, v31
	v_add_f32_e32 v98, v28, v98
	v_add_f32_e32 v98, v29, v98
	v_add_f32_e32 v98, v30, v98
	v_add_f32_e32 v159, v31, v98
	v_exp_f32_e64 v32, -v179
	v_mov_b32_e32 v160, v159
	v_mul_f32_e32 v158, v176, v32
	v_pk_mul_f32 v[34:35], v[34:35], v[32:33] op_sel_hi:[1,0]
	v_permlane32_swap_b32_e32 v159, v160
	v_pk_mul_f32 v[36:37], v[36:37], v[32:33] op_sel_hi:[1,0]
	v_pk_mul_f32 v[38:39], v[38:39], v[32:33] op_sel_hi:[1,0]
	v_pk_mul_f32 v[40:41], v[40:41], v[32:33] op_sel_hi:[1,0]
	v_pk_mul_f32 v[42:43], v[42:43], v[32:33] op_sel_hi:[1,0]
	v_pk_mul_f32 v[44:45], v[44:45], v[32:33] op_sel_hi:[1,0]
	v_pk_mul_f32 v[46:47], v[46:47], v[32:33] op_sel_hi:[1,0]
	v_pk_mul_f32 v[48:49], v[48:49], v[32:33] op_sel_hi:[1,0]
	v_pk_mul_f32 v[50:51], v[50:51], v[32:33] op_sel_hi:[1,0]
	v_pk_mul_f32 v[52:53], v[52:53], v[32:33] op_sel_hi:[1,0]
	v_pk_mul_f32 v[54:55], v[54:55], v[32:33] op_sel_hi:[1,0]
	v_pk_mul_f32 v[56:57], v[56:57], v[32:33] op_sel_hi:[1,0]
	v_pk_mul_f32 v[58:59], v[58:59], v[32:33] op_sel_hi:[1,0]
	v_pk_mul_f32 v[60:61], v[60:61], v[32:33] op_sel_hi:[1,0]
	v_pk_mul_f32 v[62:63], v[62:63], v[32:33] op_sel_hi:[1,0]
	v_pk_mul_f32 v[64:65], v[64:65], v[32:33] op_sel_hi:[1,0]
	v_add_f32_e32 v178, v159, v160
	v_mov_b32_e32 v159, v177
	s_nop 0
	v_pk_add_f32 v[178:179], v[158:159], v[178:179]
	s_branch .Lfx_pv
; #define MFMA32(a, b, c) __builtin_amdgcn_mfma_f32_32x32x16_bf16((a), (b), (c), 0, 0, 0)
; DI unsigned pk2(float a, float b) { f2_t v = {a, b}; bf2_t r = __builtin_convertvector(v, bf2_t); return __builtin_bit_cast(unsigned, r); }
; DI float ex2(float x) { return __builtin_amdgcn_exp2f(x); }
; DI float shx32(float v) { return shx(v, get_tid() & 63, 32); }
; template <int MODE>
; DI void attn_item(const CP& p, int l, int b, int head, int qt, char* smem) {
;     ...
;         if (__builtin_amdgcn_ballot_w64(d != 0.f) == 0ull) {
; #pragma unroll
;           for (int rb = 0; rb < 2; ++rb)
; #pragma unroll
;             for (int r = 0; r < 16; ++r) { const float e = ex2(s[rb][r]); s[rb][r] = e; sum += e; }
;           sum += shx32(sum);
;           lsum += sum;
;     ...
;       bf16x8 pf[4];
; #pragma unroll
;       for (int j = 0; j < 4; ++j) {
;         const int rb = j >> 1, r0 = (j & 1) * 8;
;         u32x4 u;
;         u.x = pk2(s[rb][r0], s[rb][r0 + 1]);
;         u.y = pk2(s[rb][r0 + 2], s[rb][r0 + 3]);
;         u.z = pk2(s[rb][r0 + 4], s[rb][r0 + 5]);
;         u.w = pk2(s[rb][r0 + 6], s[rb][r0 + 7]);
;         pf[j] = __builtin_bit_cast(bf16x8, u);
;       }
; #pragma unroll
;       for (int db = 0; db < 2; ++db)
; #pragma unroll
;         for (int j = 0; j < 4; ++j) {
;           const u16* vp = cV + (db * 32 + l32) * 72 + 16 * j + 4 * hh;
;           u32x2 lo = *(const u32x2*)(vp);
;           u32x2 hi = *(const u32x2*)(vp + 8);
;           u32x4 u = {lo.x, lo.y, hi.x, hi.y};
;           o[db] = MFMA32(__builtin_bit_cast(bf16x8, u), pf[j], o[db]);
;         }
.Lfx_norescale:
	v_exp_f32_e32 v0, v66
	v_exp_f32_e32 v1, v67
	v_exp_f32_e32 v2, v68
	v_exp_f32_e32 v3, v69
	v_add_f32_e32 v4, 0, v0
	v_add_f32_e32 v4, v1, v4
	v_add_f32_e32 v4, v2, v4
	v_add_f32_e32 v8, v3, v4
	v_exp_f32_e32 v4, v70
	v_exp_f32_e32 v5, v71
	v_exp_f32_e32 v6, v72
	v_exp_f32_e32 v7, v73
	v_add_f32_e32 v8, v4, v8
	v_add_f32_e32 v8, v5, v8
	v_add_f32_e32 v8, v6, v8
	v_add_f32_e32 v12, v7, v8
	v_exp_f32_e32 v8, v74
	v_exp_f32_e32 v9, v75
	v_exp_f32_e32 v10, v76
	v_exp_f32_e32 v11, v77
	v_add_f32_e32 v12, v8, v12
	v_add_f32_e32 v12, v9, v12
	v_add_f32_e32 v12, v10, v12
	v_add_f32_e32 v16, v11, v12
	v_exp_f32_e32 v12, v78
	v_exp_f32_e32 v13, v79
	v_exp_f32_e32 v14, v80
	v_exp_f32_e32 v15, v81
	v_add_f32_e32 v16, v12, v16
	v_add_f32_e32 v16, v13, v16
	v_add_f32_e32 v16, v14, v16
	v_add_f32_e32 v20, v15, v16
	v_exp_f32_e32 v16, v82
	v_exp_f32_e32 v17, v83
	v_exp_f32_e32 v18, v84
	v_exp_f32_e32 v19, v85
	v_add_f32_e32 v20, v16, v20
	v_add_f32_e32 v20, v17, v20
	v_add_f32_e32 v20, v18, v20
	v_add_f32_e32 v24, v19, v20
	v_exp_f32_e32 v20, v86
	v_exp_f32_e32 v21, v87
	v_exp_f32_e32 v22, v88
	v_exp_f32_e32 v23, v89
	v_add_f32_e32 v24, v20, v24
	v_add_f32_e32 v24, v21, v24
	v_add_f32_e32 v24, v22, v24
	v_add_f32_e32 v28, v23, v24
	v_exp_f32_e32 v24, v90
	v_exp_f32_e32 v25, v91
	v_exp_f32_e32 v26, v92
	v_exp_f32_e32 v27, v93
	v_add_f32_e32 v28, v24, v28
	v_add_f32_e32 v28, v25, v28
	v_add_f32_e32 v28, v26, v28
	v_add_f32_e32 v32, v27, v28
	v_exp_f32_e32 v28, v94
	v_exp_f32_e32 v29, v95
	v_exp_f32_e32 v30, v96
	v_exp_f32_e32 v31, v97
	v_add_f32_e32 v32, v28, v32
	v_add_f32_e32 v32, v29, v32
	v_add_f32_e32 v32, v30, v32
	v_add_f32_e32 v32, v31, v32
	v_mov_b32_e32 v66, v32
	s_nop 1
	v_permlane32_swap_b32_e32 v32, v66
	v_add_f32_e32 v32, v32, v66
	v_add_f32_e32 v176, v176, v32
	v_mov_b64_e32 v[178:179], v[176:177]
.Lfx_pv:
	v_cvt_pk_bf16_f32 v0, v0, v1
	v_cvt_pk_bf16_f32 v1, v2, v3
	v_cvt_pk_bf16_f32 v2, v4, v5
	v_cvt_pk_bf16_f32 v3, v6, v7
	v_cvt_pk_bf16_f32 v4, v8, v9
	v_cvt_pk_bf16_f32 v5, v10, v11
	v_cvt_pk_bf16_f32 v6, v12, v13
	v_cvt_pk_bf16_f32 v7, v14, v15
	v_cvt_pk_bf16_f32 v8, v16, v17
	v_cvt_pk_bf16_f32 v9, v18, v19
	v_cvt_pk_bf16_f32 v10, v20, v21
	v_cvt_pk_bf16_f32 v11, v22, v23
	v_cvt_pk_bf16_f32 v12, v24, v25
	v_cvt_pk_bf16_f32 v13, v26, v27
	v_cvt_pk_bf16_f32 v14, v28, v29
	v_cvt_pk_bf16_f32 v15, v30, v31
	s_andn2_b64 s[72:73], s[72:73], exec
	v_mov_b64_e32 v[176:177], v[178:179]
	s_waitcnt lgkmcnt(0)
	v_mfma_f32_32x32x16_bf16 v[50:65], v[216:219], v[0:3], v[50:65]
	v_mfma_f32_32x32x16_bf16 v[50:65], v[220:223], v[4:7], v[50:65]
	v_mfma_f32_32x32x16_bf16 v[50:65], v[224:227], v[8:11], v[50:65]
	v_mfma_f32_32x32x16_bf16 v[50:65], v[228:231], v[12:15], v[50:65]
	v_mfma_f32_32x32x16_bf16 v[34:49], v[232:235], v[0:3], v[34:49]
	v_mfma_f32_32x32x16_bf16 v[34:49], v[236:239], v[4:7], v[34:49]
	v_mfma_f32_32x32x16_bf16 v[34:49], v[240:243], v[8:11], v[34:49]
	v_mfma_f32_32x32x16_bf16 v[34:49], v[244:247], v[12:15], v[34:49]

; #define MFMA32(a, b, c) __builtin_amdgcn_mfma_f32_32x32x16_bf16((a), (b), (c), 0, 0, 0)
; DI void ssm_xend_item(const CP& p, int l, int item, char* smem) {
;     ...
; #pragma unroll 8
;   for (int ks = kh * 32; ks < kh * 32 + 32; ++ks) {
;     const bf16x8 fa = *(const bf16x8*)(wp + ks * 16);
;     const bf16x8 fb = *(const bf16x8*)(up + (size_t)ks * TMW);
;     acc = MFMA32(fa, fb, acc);
;   }
;   float* red = (float*)smem;
;   if (kh == 1) {
; #pragma unroll
;     for (int r = 0; r < 16; ++r) red[(mb * 16 + r) * 64 + lane] = acc[r];
;   }
.LBB0_412:
	v_lshl_add_u64 v[30:31], v[18:19], 0, v[32:33]
	v_lshl_add_u64 v[38:39], v[16:17], 0, v[32:33]
	s_mov_b64 s[10:11], 0x1000
	v_lshl_add_u64 v[40:41], v[38:39], 0, s[10:11]
	s_mov_b64 s[10:11], 0x2000
	v_lshl_add_u64 v[42:43], v[38:39], 0, s[10:11]
	s_mov_b64 s[10:11], 0x3000
	v_lshl_add_u64 v[108:109], v[38:39], 0, s[10:11]
	s_mov_b64 s[10:11], 0x4000
	v_lshl_add_u64 v[110:111], v[38:39], 0, s[10:11]
	s_mov_b64 s[10:11], 0x5000
	v_lshl_add_u64 v[112:113], v[38:39], 0, s[10:11]
	s_mov_b64 s[10:11], 0x6000
	v_lshl_add_u64 v[114:115], v[38:39], 0, s[10:11]
	global_load_dwordx4 v[44:47], v[30:31], off
	global_load_dwordx4 v[76:79], v[38:39], off offset:2816
	global_load_dwordx4 v[48:51], v[30:31], off offset:32
	global_load_dwordx4 v[80:83], v[40:41], off offset:2048
	global_load_dwordx4 v[52:55], v[30:31], off offset:64
	global_load_dwordx4 v[84:87], v[42:43], off offset:1280
	global_load_dwordx4 v[56:59], v[30:31], off offset:96
	global_load_dwordx4 v[88:91], v[108:109], off offset:512
	global_load_dwordx4 v[60:63], v[30:31], off offset:128
	global_load_dwordx4 v[92:95], v[108:109], off offset:3840
	global_load_dwordx4 v[64:67], v[30:31], off offset:160
	global_load_dwordx4 v[96:99], v[110:111], off offset:3072
	global_load_dwordx4 v[68:71], v[30:31], off offset:192
	global_load_dwordx4 v[100:103], v[112:113], off offset:2304
	global_load_dwordx4 v[72:75], v[30:31], off offset:224
	global_load_dwordx4 v[104:107], v[114:115], off offset:1536
	s_add_i32 s4, s4, -8
	s_mov_b64 s[10:11], 0x6800
	v_lshl_add_u64 v[16:17], v[16:17], 0, s[10:11]
	v_lshl_add_u64 v[18:19], v[18:19], 0, s[52:53]
	s_waitcnt vmcnt(14)
	v_mfma_f32_32x32x16_bf16 v[0:15], v[44:47], v[76:79], v[0:15]
	s_waitcnt vmcnt(12)
	v_mfma_f32_32x32x16_bf16 v[0:15], v[48:51], v[80:83], v[0:15]
	s_waitcnt vmcnt(10)
	v_mfma_f32_32x32x16_bf16 v[0:15], v[52:55], v[84:87], v[0:15]
	s_waitcnt vmcnt(8)
	v_mfma_f32_32x32x16_bf16 v[0:15], v[56:59], v[88:91], v[0:15]
	s_waitcnt vmcnt(6)
	v_mfma_f32_32x32x16_bf16 v[0:15], v[60:63], v[92:95], v[0:15]
	s_waitcnt vmcnt(4)
	v_mfma_f32_32x32x16_bf16 v[0:15], v[64:67], v[96:99], v[0:15]
	s_waitcnt vmcnt(2)
	v_mfma_f32_32x32x16_bf16 v[0:15], v[68:71], v[100:103], v[0:15]
	s_waitcnt vmcnt(0)
	v_mfma_f32_32x32x16_bf16 v[0:15], v[72:75], v[104:107], v[0:15]
	s_cmp_eq_u32 s4, 0
	s_cbranch_scc0 .LBB0_412
	v_and_b32_e32 v16, 63, v21
	v_cmp_eq_u32_e32 vcc, 1, v24
	v_lshlrev_b32_e32 v16, 2, v16
	s_and_saveexec_b64 s[4:5], vcc
	s_cbranch_execz .LBB0_415
	v_lshlrev_b32_e32 v17, 12, v23
	v_add3_u32 v17, 0, v17, v16
	s_nop 3
	ds_write2st64_b32 v17, v0, v1 offset1:1
	ds_write2st64_b32 v17, v2, v3 offset0:2 offset1:3
	ds_write2st64_b32 v17, v4, v5 offset0:4 offset1:5
	ds_write2st64_b32 v17, v6, v7 offset0:6 offset1:7
	ds_write2st64_b32 v17, v8, v9 offset0:8 offset1:9
	ds_write2st64_b32 v17, v10, v11 offset0:10 offset1:11
	ds_write2st64_b32 v17, v12, v13 offset0:12 offset1:13
	ds_write2st64_b32 v17, v14, v15 offset0:14 offset1:15
